# ATTN ping-pong + row sums as VALU adds at the start of the next LOAD segment (4 fewer MFMAs per tile in COMPUTE)
# baseline (speedup 1.0000x reference)
.LBB0_946:
	s_add_i32 s35, s15, -2
	s_add_i32 s36, s35, -1
	s_cmp_gt_u32 s36, s28
	s_cbranch_scc1 .Lp3_pe
	v_add_f32_e32 v16, v16, v66
	v_add_f32_e32 v17, v17, v67
	v_add_f32_e32 v180, v180, v68
	v_add_f32_e32 v181, v181, v69
	v_add_f32_e32 v16, v16, v70
	v_add_f32_e32 v17, v17, v71
	v_add_f32_e32 v180, v180, v72
	v_add_f32_e32 v181, v181, v73
	v_add_f32_e32 v16, v16, v74
	v_add_f32_e32 v17, v17, v75
	v_add_f32_e32 v180, v180, v76
	v_add_f32_e32 v181, v181, v77
	v_add_f32_e32 v16, v16, v78
	v_add_f32_e32 v17, v17, v79
	v_add_f32_e32 v180, v180, v80
	v_add_f32_e32 v181, v181, v81
	v_add_f32_e32 v16, v16, v82
	v_add_f32_e32 v17, v17, v83
	v_add_f32_e32 v180, v180, v84
	v_add_f32_e32 v181, v181, v85
	v_add_f32_e32 v16, v16, v86
	v_add_f32_e32 v17, v17, v87
	v_add_f32_e32 v180, v180, v88
	v_add_f32_e32 v181, v181, v89
	v_add_f32_e32 v16, v16, v90
	v_add_f32_e32 v17, v17, v91
	v_add_f32_e32 v180, v180, v92
	v_add_f32_e32 v181, v181, v93
	v_add_f32_e32 v16, v16, v94
	v_add_f32_e32 v17, v17, v95
	v_add_f32_e32 v180, v180, v96
	v_add_f32_e32 v181, v181, v97

.LBB0_952:
	s_lshl_b32 s6, s5, 8
	s_add_i32 s14, s6, s16
	s_add_u32 s12, s8, s14
	s_addc_u32 s13, s9, 0
	s_lshl_b64 s[6:7], s[12:13], 10
	v_lshl_add_u64 v[4:5], v[114:115], 0, s[6:7]
	s_mov_b32 s15, s11
	global_load_dwordx4 v[98:101], v[4:5], off offset:32
	global_load_dwordx4 v[102:105], v[4:5], off offset:64
	global_load_dwordx4 v[106:109], v[4:5], off offset:96
	v_lshl_add_u64 v[136:137], s[14:15], 3, v[120:121]
	global_load_dwordx4 v[110:113], v[4:5], off
	global_load_dwordx2 v[138:139], v[136:137], off
	s_waitcnt lgkmcnt(0)
	s_barrier
	s_mov_b32 m0, s21
	global_load_lds_dwordx4 v[116:117], off
	s_mov_b32 m0, s22
	global_load_lds_dwordx4 v[118:119], off
	v_mov_b32_e32 v16, v2
	s_mov_b32 m0, s23
	global_load_lds_dwordx4 v[122:123], off
	s_mov_b32 m0, s24
	global_load_lds_dwordx4 v[124:125], off
	s_waitcnt vmcnt(2)
	v_mov_b32_e32 v17, v2
	s_lshl_b32 s6, s5, 2
	s_lshl_b32 s30, s5, 10
	v_mov_b32_e32 v3, v2
	v_mov_b32_e32 v4, v2
	v_mov_b32_e32 v5, v2
	v_mov_b32_e32 v6, v2
	v_mov_b32_e32 v7, v2
	v_mov_b32_e32 v8, v2
	v_mov_b32_e32 v9, v2
	v_mov_b32_e32 v10, v2
	v_mov_b32_e32 v11, v2
	v_mov_b32_e32 v12, v2
	v_mov_b32_e32 v13, v2
	v_mov_b32_e32 v14, v2
	v_mov_b32_e32 v15, v2
	v_mov_b64_e32 v[48:49], v[16:17]
	v_mov_b64_e32 v[32:33], v[16:17]
	v_mov_b64_e32 v[64:65], v[16:17]
	s_mov_b32 s15, 2
	s_add_i32 s27, s6, 4
	s_lshr_b32 s28, s14, 6
	s_or_b32 s29, s6, 3
	v_add_u32_e32 v148, s30, v142
	s_addk_i32 s30, 0x400
	s_mov_b32 s31, 0
	s_movk_i32 s33, 0xaf
	v_mov_b64_e32 v[46:47], v[14:15]
	v_mov_b64_e32 v[44:45], v[12:13]
	v_mov_b64_e32 v[42:43], v[10:11]
	v_mov_b64_e32 v[40:41], v[8:9]
	v_mov_b64_e32 v[38:39], v[6:7]
	v_mov_b64_e32 v[36:37], v[4:5]
	v_mov_b64_e32 v[34:35], v[2:3]
	v_mov_b64_e32 v[30:31], v[14:15]
	v_mov_b64_e32 v[28:29], v[12:13]
	v_mov_b64_e32 v[26:27], v[10:11]
	v_mov_b64_e32 v[24:25], v[8:9]
	v_mov_b64_e32 v[22:23], v[6:7]
	v_mov_b64_e32 v[20:21], v[4:5]
	v_mov_b64_e32 v[18:19], v[2:3]
	v_mov_b64_e32 v[62:63], v[14:15]
	v_mov_b64_e32 v[60:61], v[12:13]
	v_mov_b64_e32 v[58:59], v[10:11]
	v_mov_b64_e32 v[56:57], v[8:9]
	v_mov_b64_e32 v[54:55], v[6:7]
	v_mov_b64_e32 v[52:53], v[4:5]
	v_mov_b64_e32 v[50:51], v[2:3]
	s_mov_b32 s34, 0
	v_mov_b32_e32 v16, 0
	v_mov_b32_e32 v17, 0
	v_mov_b32_e32 v180, 0
	v_mov_b32_e32 v181, 0
	s_cmp_lt_u32 s93, 4
	s_cbranch_scc1 .Lpp_pre
	s_barrier

.LBB0_955:
	s_add_i32 s35, s15, -2
	s_lshl_b32 s5, s34, 13
	s_cmp_lt_u32 s15, s27
	s_cselect_b32 s10, s15, s29
	s_lshl_b64 s[6:7], s[10:11], 16
	s_waitcnt vmcnt(0)
	v_lshrrev_b32_e32 v3, v1, v138
	v_lshl_add_u64 v[6:7], v[116:117], 0, s[6:7]
	v_lshl_add_u64 v[8:9], v[118:119], 0, s[6:7]
	s_add_i32 s6, s5, 0xffffe000
	v_lshlrev_b32_e32 v3, 4, v3
	s_cmp_lg_u32 s34, 0
	v_and_b32_e32 v4, 0xf0f0f0f0, v3
	v_lshrrev_b32_e32 v3, v1, v139
	s_cselect_b32 s6, s6, 0x4000
	v_lshlrev_b32_e32 v3, 4, v3
	s_add_i32 s6, s6, 0
	v_and_b32_e32 v3, 0xf0f0f0f0, v3
	s_add_i32 s6, s20, s6
	s_waitcnt lgkmcnt(0)
	s_barrier
	s_add_i32 s7, s6, 0x6000
	s_mov_b32 m0, s6
	global_load_lds_dwordx4 v[6:7], off
	s_mov_b32 m0, s7
	global_load_lds_dwordx4 v[8:9], off
	s_add_i32 s6, s15, -1
	s_cmp_lt_u32 s35, 63
	s_cselect_b32 s10, s6, 63
	s_lshl_b64 s[6:7], s[10:11], 15
	v_lshl_add_u64 v[6:7], v[136:137], 0, s[6:7]
	global_load_dwordx2 v[138:139], v[6:7], off
	s_cmp_eq_u32 s35, 0
	s_cbranch_scc1 .Lp3_ns
	s_add_i32 s36, s35, -1
	s_cmp_gt_u32 s36, s28
	s_cbranch_scc1 .Lp3_ns
	v_add_f32_e32 v16, v16, v66
	v_add_f32_e32 v17, v17, v67
	v_add_f32_e32 v180, v180, v68
	v_add_f32_e32 v181, v181, v69
	v_add_f32_e32 v16, v16, v70
	v_add_f32_e32 v17, v17, v71
	v_add_f32_e32 v180, v180, v72
	v_add_f32_e32 v181, v181, v73
	v_add_f32_e32 v16, v16, v74
	v_add_f32_e32 v17, v17, v75
	v_add_f32_e32 v180, v180, v76
	v_add_f32_e32 v181, v181, v77
	v_add_f32_e32 v16, v16, v78
	v_add_f32_e32 v17, v17, v79
	v_add_f32_e32 v180, v180, v80
	v_add_f32_e32 v181, v181, v81
	v_add_f32_e32 v16, v16, v82
	v_add_f32_e32 v17, v17, v83
	v_add_f32_e32 v180, v180, v84
	v_add_f32_e32 v181, v181, v85
	v_add_f32_e32 v16, v16, v86
	v_add_f32_e32 v17, v17, v87
	v_add_f32_e32 v180, v180, v88
	v_add_f32_e32 v181, v181, v89
	v_add_f32_e32 v16, v16, v90
	v_add_f32_e32 v17, v17, v91
	v_add_f32_e32 v180, v180, v92
	v_add_f32_e32 v181, v181, v93
	v_add_f32_e32 v16, v16, v94
	v_add_f32_e32 v17, v17, v95
	v_add_f32_e32 v180, v180, v96
	v_add_f32_e32 v181, v181, v97
.Lp3_ns:
	s_cmp_gt_u32 s35, s28
	s_cbranch_scc1 .Lpp_skip
	v_add_u32_e32 v149, s5, v140
	v_add_u32_e32 v150, s5, v141
	v_add_u32_sdwa v230, v4, s25 dst_sel:DWORD dst_unused:UNUSED_PAD src0_sel:BYTE_0 src1_sel:DWORD
	v_add_u32_sdwa v231, v4, s25 dst_sel:DWORD dst_unused:UNUSED_PAD src0_sel:BYTE_1 src1_sel:DWORD
	v_add_u32_sdwa v232, v4, s25 dst_sel:DWORD dst_unused:UNUSED_PAD src0_sel:BYTE_2 src1_sel:DWORD
	v_add_u32_sdwa v233, v4, s25 dst_sel:DWORD dst_unused:UNUSED_PAD src0_sel:BYTE_3 src1_sel:DWORD
	v_add_u32_sdwa v234, v3, s25 dst_sel:DWORD dst_unused:UNUSED_PAD src0_sel:BYTE_0 src1_sel:DWORD
	v_add_u32_sdwa v235, v3, s25 dst_sel:DWORD dst_unused:UNUSED_PAD src0_sel:BYTE_1 src1_sel:DWORD
	v_add_u32_sdwa v236, v3, s25 dst_sel:DWORD dst_unused:UNUSED_PAD src0_sel:BYTE_2 src1_sel:DWORD
	v_add_u32_sdwa v237, v3, s25 dst_sel:DWORD dst_unused:UNUSED_PAD src0_sel:BYTE_3 src1_sel:DWORD
	ds_read_b128 v[66:69], v230
	ds_read_b128 v[70:73], v231
	ds_read_b128 v[74:77], v232
	ds_read_b128 v[78:81], v233
	ds_read_b128 v[182:185], v149
	ds_read_b128 v[186:189], v149 offset:2048
	ds_read_b128 v[190:193], v149 offset:4096
	ds_read_b128 v[194:197], v149 offset:6144
	ds_read_b128 v[82:85], v234
	ds_read_b128 v[86:89], v235
	ds_read_b128 v[90:93], v236
	ds_read_b128 v[94:97], v237
	s_waitcnt lgkmcnt(8)
	ds_read_b128 v[198:201], v149 offset:512
	ds_read_b128 v[202:205], v149 offset:2560
	ds_read_b128 v[206:209], v149 offset:4608
	ds_read_b128 v[210:213], v149 offset:6656
	s_waitcnt lgkmcnt(8)
	ds_read_b64_tr_b16 v[152:153], v150
	ds_read_b64_tr_b16 v[154:155], v150 offset:512
	ds_read_b64_tr_b16 v[156:157], v150 offset:1024
	ds_read_b64_tr_b16 v[158:159], v150 offset:1536
	s_waitcnt lgkmcnt(8)
	ds_read_b64_tr_b16 v[160:161], v150 offset:2048
	ds_read_b64_tr_b16 v[162:163], v150 offset:2560
	ds_read_b64_tr_b16 v[164:165], v150 offset:3072
	ds_read_b64_tr_b16 v[166:167], v150 offset:3584
	s_waitcnt lgkmcnt(8)
	ds_read_b64_tr_b16 v[168:169], v150 offset:4096
	ds_read_b64_tr_b16 v[170:171], v150 offset:4608
	ds_read_b64_tr_b16 v[172:173], v150 offset:5120
	ds_read_b64_tr_b16 v[174:175], v150 offset:5632
	s_waitcnt lgkmcnt(8)
	ds_read_b64_tr_b16 v[214:215], v150 offset:6144
	ds_read_b64_tr_b16 v[216:217], v150 offset:6656
	ds_read_b64_tr_b16 v[218:219], v150 offset:7168
	ds_read_b64_tr_b16 v[220:221], v150 offset:7680
	s_waitcnt lgkmcnt(0)
	s_barrier
	v_mfma_f32_32x32x16_bf16 v[66:81], v[182:185], v[110:113], v[66:81]
	v_mfma_f32_32x32x16_bf16 v[66:81], v[186:189], v[98:101], v[66:81]
	v_mfma_f32_32x32x16_bf16 v[66:81], v[190:193], v[102:105], v[66:81]
	v_mfma_f32_32x32x16_bf16 v[66:81], v[194:197], v[106:109], v[66:81]
	s_cmp_lt_u32 s33, s14
	s_cbranch_scc0 .Lp3_bias
	v_mfma_f32_32x32x16_bf16 v[82:97], v[198:201], v[110:113], v[82:97]
	v_mfma_f32_32x32x16_bf16 v[82:97], v[202:205], v[98:101], v[82:97]
	s_nop 7
	s_nop 1
	v_exp_f32_e32 v66, v66
	v_exp_f32_e32 v67, v67
	v_exp_f32_e32 v68, v68
	v_exp_f32_e32 v69, v69
	v_mfma_f32_32x32x16_bf16 v[82:97], v[206:209], v[102:105], v[82:97]
	v_exp_f32_e32 v70, v70
	v_exp_f32_e32 v71, v71
	v_exp_f32_e32 v72, v72
	v_exp_f32_e32 v73, v73
	v_mfma_f32_32x32x16_bf16 v[82:97], v[210:213], v[106:109], v[82:97]
	v_exp_f32_e32 v74, v74
	v_exp_f32_e32 v75, v75
	v_exp_f32_e32 v76, v76
	v_exp_f32_e32 v77, v77
	v_exp_f32_e32 v78, v78
	v_exp_f32_e32 v79, v79
	v_exp_f32_e32 v80, v80
	v_exp_f32_e32 v81, v81
	v_cvt_pk_bf16_f32 v4, v66, v67
	v_cvt_pk_bf16_f32 v5, v68, v69
	v_cvt_pk_bf16_f32 v6, v70, v71
	v_cvt_pk_bf16_f32 v7, v72, v73
	v_cvt_pk_bf16_f32 v8, v74, v75
	v_cvt_pk_bf16_f32 v9, v76, v77
	v_cvt_pk_bf16_f32 v10, v78, v79
	v_cvt_pk_bf16_f32 v11, v80, v81
	v_mfma_f32_32x32x16_bf16 v[34:49], v[4:7], v[152:155], v[34:49]
	v_exp_f32_e32 v82, v82
	v_exp_f32_e32 v83, v83
	v_exp_f32_e32 v84, v84
	v_exp_f32_e32 v85, v85
	v_mfma_f32_32x32x16_bf16 v[18:33], v[4:7], v[168:171], v[18:33]
	v_exp_f32_e32 v86, v86
	v_exp_f32_e32 v87, v87
	v_exp_f32_e32 v88, v88
	v_exp_f32_e32 v89, v89
	v_mfma_f32_32x32x16_bf16 v[34:49], v[8:11], v[156:159], v[34:49]
	v_exp_f32_e32 v90, v90
	v_exp_f32_e32 v91, v91
	v_exp_f32_e32 v92, v92
	v_exp_f32_e32 v93, v93
	v_mfma_f32_32x32x16_bf16 v[18:33], v[8:11], v[172:175], v[18:33]
	v_exp_f32_e32 v94, v94
	v_exp_f32_e32 v95, v95
	v_exp_f32_e32 v96, v96
	v_exp_f32_e32 v97, v97
	v_cvt_pk_bf16_f32 v12, v82, v83
	v_cvt_pk_bf16_f32 v13, v84, v85
	v_cvt_pk_bf16_f32 v14, v86, v87
	v_cvt_pk_bf16_f32 v15, v88, v89
	v_cvt_pk_bf16_f32 v222, v90, v91
	v_cvt_pk_bf16_f32 v223, v92, v93
	v_cvt_pk_bf16_f32 v224, v94, v95
	v_cvt_pk_bf16_f32 v225, v96, v97
	s_nop 1
	v_mfma_f32_32x32x16_bf16 v[34:49], v[12:15], v[160:163], v[34:49]
	v_mfma_f32_32x32x16_bf16 v[18:33], v[12:15], v[214:217], v[18:33]
	v_mfma_f32_32x32x16_bf16 v[34:49], v[222:225], v[164:167], v[34:49]
	v_mfma_f32_32x32x16_bf16 v[18:33], v[222:225], v[218:221], v[18:33]
	s_branch .LBB0_954
.Lp3_bias:
	v_mfma_f32_32x32x16_bf16 v[82:97], v[198:201], v[110:113], v[82:97]
	v_mfma_f32_32x32x16_bf16 v[82:97], v[202:205], v[98:101], v[82:97]
	v_mfma_f32_32x32x16_bf16 v[82:97], v[206:209], v[102:105], v[82:97]
	v_mfma_f32_32x32x16_bf16 v[82:97], v[210:213], v[106:109], v[82:97]
	v_add_u32_e32 v3, s31, v148
	v_add_u32_e32 v4, 0x149fc, v3
	v_add_u32_e32 v6, 0x1497c, v3
	v_add_u32_e32 v8, 0x149f4, v3
	ds_read2_b32 v[4:5], v4 offset1:1
	ds_read2_b32 v[6:7], v6 offset1:1
	ds_read2_b32 v[8:9], v8 offset1:1
	v_add_u32_e32 v10, 0x14974, v3
	v_add_u32_e32 v12, 0x14954, v3
	s_waitcnt lgkmcnt(2)
	v_pk_add_f32 v[66:67], v[66:67], v[4:5] op_sel:[0,1] op_sel_hi:[1,0]
	s_waitcnt lgkmcnt(1)
	v_pk_add_f32 v[82:83], v[82:83], v[6:7] op_sel:[0,1] op_sel_hi:[1,0]
	s_waitcnt lgkmcnt(0)
	v_pk_add_f32 v[68:69], v[68:69], v[8:9] op_sel:[0,1] op_sel_hi:[1,0]
	v_add_u32_e32 v4, 0x149dc, v3
	v_add_u32_e32 v6, 0x1495c, v3
	v_add_u32_e32 v8, 0x149d4, v3
	ds_read2_b32 v[10:11], v10 offset1:1
	ds_read2_b32 v[4:5], v4 offset1:1
	ds_read2_b32 v[6:7], v6 offset1:1
	ds_read2_b32 v[8:9], v8 offset1:1
	ds_read2_b32 v[12:13], v12 offset1:1
	s_waitcnt lgkmcnt(3)
	v_pk_add_f32 v[70:71], v[70:71], v[4:5] op_sel:[0,1] op_sel_hi:[1,0]
	s_waitcnt lgkmcnt(2)
	v_pk_add_f32 v[86:87], v[86:87], v[6:7] op_sel:[0,1] op_sel_hi:[1,0]
	s_waitcnt lgkmcnt(1)
	v_pk_add_f32 v[72:73], v[72:73], v[8:9] op_sel:[0,1] op_sel_hi:[1,0]
	v_add_u32_e32 v4, 0x149bc, v3
	v_add_u32_e32 v6, 0x1493c, v3
	v_add_u32_e32 v8, 0x149b4, v3
	ds_read2_b32 v[4:5], v4 offset1:1
	ds_read2_b32 v[6:7], v6 offset1:1
	ds_read2_b32 v[8:9], v8 offset1:1
	v_pk_add_f32 v[84:85], v[84:85], v[10:11] op_sel:[0,1] op_sel_hi:[1,0]
	v_add_u32_e32 v10, 0x14934, v3
	s_waitcnt lgkmcnt(2)
	v_pk_add_f32 v[74:75], v[74:75], v[4:5] op_sel:[0,1] op_sel_hi:[1,0]
	s_waitcnt lgkmcnt(1)
	v_pk_add_f32 v[90:91], v[90:91], v[6:7] op_sel:[0,1] op_sel_hi:[1,0]
	s_waitcnt lgkmcnt(0)
	v_pk_add_f32 v[76:77], v[76:77], v[8:9] op_sel:[0,1] op_sel_hi:[1,0]
	v_add_u32_e32 v4, 0x1499c, v3
	v_add_u32_e32 v6, 0x1491c, v3
	v_add_u32_e32 v8, 0x14994, v3
	v_pk_add_f32 v[88:89], v[88:89], v[12:13] op_sel:[0,1] op_sel_hi:[1,0]
	ds_read2_b32 v[10:11], v10 offset1:1
	v_add_u32_e32 v3, 0x14914, v3
	ds_read2_b32 v[4:5], v4 offset1:1
	ds_read2_b32 v[6:7], v6 offset1:1
	ds_read2_b32 v[8:9], v8 offset1:1
	ds_read2_b32 v[12:13], v3 offset1:1
	s_waitcnt lgkmcnt(3)
	v_pk_add_f32 v[78:79], v[78:79], v[4:5] op_sel:[0,1] op_sel_hi:[1,0]
	v_pk_add_f32 v[92:93], v[92:93], v[10:11] op_sel:[0,1] op_sel_hi:[1,0]
	s_waitcnt lgkmcnt(2)
	v_pk_add_f32 v[94:95], v[94:95], v[6:7] op_sel:[0,1] op_sel_hi:[1,0]
	s_waitcnt lgkmcnt(1)
	v_pk_add_f32 v[80:81], v[80:81], v[8:9] op_sel:[0,1] op_sel_hi:[1,0]
	s_waitcnt lgkmcnt(0)
	v_pk_add_f32 v[96:97], v[96:97], v[12:13] op_sel:[0,1] op_sel_hi:[1,0]
	v_exp_f32_e32 v66, v66
	v_exp_f32_e32 v67, v67
	v_exp_f32_e32 v68, v68
	v_exp_f32_e32 v69, v69
	v_exp_f32_e32 v70, v70
	v_exp_f32_e32 v71, v71
	v_exp_f32_e32 v72, v72
	v_exp_f32_e32 v73, v73
	v_exp_f32_e32 v74, v74
	v_exp_f32_e32 v75, v75
	v_exp_f32_e32 v76, v76
	v_exp_f32_e32 v77, v77
	v_exp_f32_e32 v78, v78
	v_exp_f32_e32 v79, v79
	v_exp_f32_e32 v80, v80
	v_exp_f32_e32 v81, v81
	v_cvt_pk_bf16_f32 v4, v66, v67
	v_cvt_pk_bf16_f32 v5, v68, v69
	v_cvt_pk_bf16_f32 v6, v70, v71
	v_cvt_pk_bf16_f32 v7, v72, v73
	v_cvt_pk_bf16_f32 v8, v74, v75
	v_cvt_pk_bf16_f32 v9, v76, v77
	v_cvt_pk_bf16_f32 v10, v78, v79
	v_cvt_pk_bf16_f32 v11, v80, v81
	v_mfma_f32_32x32x16_bf16 v[34:49], v[4:7], v[152:155], v[34:49]
	v_exp_f32_e32 v82, v82
	v_exp_f32_e32 v83, v83
	v_exp_f32_e32 v84, v84
	v_exp_f32_e32 v85, v85
	v_mfma_f32_32x32x16_bf16 v[18:33], v[4:7], v[168:171], v[18:33]
	v_exp_f32_e32 v86, v86
	v_exp_f32_e32 v87, v87
	v_exp_f32_e32 v88, v88
	v_exp_f32_e32 v89, v89
	v_mfma_f32_32x32x16_bf16 v[34:49], v[8:11], v[156:159], v[34:49]
	v_exp_f32_e32 v90, v90
	v_exp_f32_e32 v91, v91
	v_exp_f32_e32 v92, v92
	v_exp_f32_e32 v93, v93
	v_mfma_f32_32x32x16_bf16 v[18:33], v[8:11], v[172:175], v[18:33]
	v_exp_f32_e32 v94, v94
	v_exp_f32_e32 v95, v95
	v_exp_f32_e32 v96, v96
	v_exp_f32_e32 v97, v97
	v_cvt_pk_bf16_f32 v12, v82, v83
	v_cvt_pk_bf16_f32 v13, v84, v85
	v_cvt_pk_bf16_f32 v14, v86, v87
	v_cvt_pk_bf16_f32 v15, v88, v89
	v_cvt_pk_bf16_f32 v222, v90, v91
	v_cvt_pk_bf16_f32 v223, v92, v93
	v_cvt_pk_bf16_f32 v224, v94, v95
	v_cvt_pk_bf16_f32 v225, v96, v97
	s_nop 1
	v_mfma_f32_32x32x16_bf16 v[34:49], v[12:15], v[160:163], v[34:49]
	v_mfma_f32_32x32x16_bf16 v[18:33], v[12:15], v[214:217], v[18:33]
	v_mfma_f32_32x32x16_bf16 v[34:49], v[222:225], v[164:167], v[34:49]
	v_mfma_f32_32x32x16_bf16 v[18:33], v[222:225], v[218:221], v[18:33]
	s_branch .LBB0_954
